# same as previous but plain vmcnt(0) before each tile barrier (counted vmcnt(2) + extra tail barrier removed)
# speedup vs baseline: 1.0371x; 1.0001x over previous
; #define SBAR() __builtin_amdgcn_sched_barrier(0)
; __device__ __forceinline__ void qkt3(f32x16& p0, f32x16& p1, const bf16* Ks, const bf16x8* qr, int r32, int hi, const f32x16& cinit) {
;   { int cb = (hi * 8) * 2;
;     bf16x8 b0 = *reinterpret_cast<const bf16x8*>((const char*)Ks + KSWZ(r32, cb));
;     bf16x8 b1 = *reinterpret_cast<const bf16x8*>((const char*)Ks + KSWZ(32 + r32, cb));
;     p0 = __builtin_amdgcn_mfma_f32_32x32x16_bf16(b0, qr[0], cinit, 0, 0, 0);
;     p1 = __builtin_amdgcn_mfma_f32_32x32x16_bf16(b1, qr[0], cinit, 0, 0, 0); }
;   for (int d0 = 1; d0 < 8; ++d0) { int cb = (d0 * 16 + hi * 8) * 2;
;     bf16x8 b0 = *reinterpret_cast<const bf16x8*>((const char*)Ks + KSWZ(r32, cb));
;     bf16x8 b1 = *reinterpret_cast<const bf16x8*>((const char*)Ks + KSWZ(32 + r32, cb));
;     p0 = __builtin_amdgcn_mfma_f32_32x32x16_bf16(b0, qr[d0], p0, 0, 0, 0);
;     p1 = __builtin_amdgcn_mfma_f32_32x32x16_bf16(b1, qr[d0], p1, 0, 0, 0); }
; }
; __device__ __forceinline__ int v_st(int k, int c) { const int kk = (k & ~0xC) | ((k & 4) << 1) | ((k & 8) >> 1); return ((kk >> 3) * 4 + (c >> 5)) * 512 + ((kk & 7) * 32 + (c & 31)) * 2; }
; __device__ __forceinline__ int v_rd_base(int lane) { return ((lane & 3) << 3) | (((lane >> 2) & 3) << 6) | (((lane >> 4) & 1) << 5) | (((lane >> 5) & 1) << 8); }
; template <int OFF> __device__ __forceinline__ s16x4 tr_read(int vb) {
;   s16x4 r; asm volatile("ds_read_b64_tr_b16 %0, %1 offset:%2" : "=&v"(r) : "v"(vb), "i"(OFF) : "memory"); return r;
; }
; template <int D0> __device__ __forceinline__ void pv_one(f32x16& od, int vb, bf16x8 pa0, bf16x8 pa1, bf16x8 pa2, bf16x8 pa3) {
;   const s16x4 l0 = tr_read<v_rd_off(D0, 0, 0)>(vb), h0 = tr_read<v_rd_off(D0, 0, 1)>(vb), l1 = tr_read<v_rd_off(D0, 1, 0)>(vb), h1 = tr_read<v_rd_off(D0, 1, 1)>(vb);
;   const s16x4 l2 = tr_read<v_rd_off(D0, 2, 0)>(vb), h2 = tr_read<v_rd_off(D0, 2, 1)>(vb), l3 = tr_read<v_rd_off(D0, 3, 0)>(vb), h3 = tr_read<v_rd_off(D0, 3, 1)>(vb);
;   asm volatile("s_waitcnt lgkmcnt(0)" ::: "memory"); SBAR();
;     ...
;   od = __builtin_amdgcn_mfma_f32_32x32x16_bf16(pa0, PK(l0, h0), od, 0, 0, 0);
;   od = __builtin_amdgcn_mfma_f32_32x32x16_bf16(pa1, PK(l1, h1), od, 0, 0, 0);
;   od = __builtin_amdgcn_mfma_f32_32x32x16_bf16(pa2, PK(l2, h2), od, 0, 0, 0);
;   od = __builtin_amdgcn_mfma_f32_32x32x16_bf16(pa3, PK(l3, h3), od, 0, 0, 0);
;     ...
; }
.LBB0_117:
	s_lshl_b32 s49, s48, 14
	s_mov_b32 s53, s46
	s_mov_b32 s46, s54
	s_add_i32 s86, s90, s49
	s_and_b32 s87, s47, 2
	s_lshl_b32 s87, s87, 14
	s_add_i32 s87, s87, s90
	s_lshl_b32 s15, s53, 14
	s_lshl_b32 s14, s54, 14
	v_add_u32_e32 v238, s15, v157
	ds_read_b128 v[246:249], v238 offset:49152
	ds_read_b128 v[238:241], v238 offset:57344
	v_add_u32_e32 v228, s15, v177
	ds_read_b128 v[224:227], v228 offset:49152
	ds_read_b128 v[228:231], v228 offset:57344
	v_cvt_pk_bf16_f32 v185, v202, v204
	v_cvt_pk_bf16_f32 v191, v180, v182
	v_cvt_pk_bf16_f32 v181, v212, v214
	v_cvt_pk_bf16_f32 v187, v220, v222
	v_cvt_pk_bf16_f32 v189, v158, v166
	s_waitcnt lgkmcnt(2)
	v_mfma_f32_32x32x16_bf16 v[96:111], v[246:249], v[140:143], v[64:79]
	v_mfma_f32_32x32x16_bf16 v[80:95], v[238:241], v[140:143], v[64:79]
	v_add_u32_e32 v238, s15, v175
	ds_read_b128 v[246:249], v238 offset:49152
	ds_read_b128 v[238:241], v238 offset:57344
	s_add_i32 m0, s86, 0xc000
	s_nop 0
	global_load_lds_dwordx4 v154, s[40:41]
	v_add_f32_e32 v162, 0, v179
	v_add_f32_e32 v162, v170, v162
	v_add_f32_e32 v162, v172, v162
	v_add_f32_e32 v162, v174, v162
	s_waitcnt lgkmcnt(2)
	v_mfma_f32_32x32x16_bf16 v[96:111], v[224:227], v[136:139], v[96:111]
	v_mfma_f32_32x32x16_bf16 v[80:95], v[228:231], v[136:139], v[80:95]
	v_add_u32_e32 v228, s15, v173
	ds_read_b128 v[224:227], v228 offset:49152
	ds_read_b128 v[228:231], v228 offset:57344
	v_add_f32_e32 v162, v184, v162
	v_add_f32_e32 v162, v186, v162
	v_add_f32_e32 v162, v188, v162
	v_add_f32_e32 v162, v190, v162
	s_waitcnt lgkmcnt(2)
	v_mfma_f32_32x32x16_bf16 v[96:111], v[246:249], v[132:135], v[96:111]
	v_mfma_f32_32x32x16_bf16 v[80:95], v[238:241], v[132:135], v[80:95]
	v_add_u32_e32 v238, s15, v171
	ds_read_b128 v[246:249], v238 offset:49152
	ds_read_b128 v[238:241], v238 offset:57344
	s_add_i32 m0, s86, 0xc400
	s_nop 0
	global_load_lds_dwordx4 v152, s[40:41]
	s_add_u32 s40, s40, 0x8000
	s_addc_u32 s41, s41, 0
	v_add_f32_e32 v162, v206, v162
	v_add_f32_e32 v162, v200, v162
	v_add_f32_e32 v162, v202, v162
	v_add_f32_e32 v162, v204, v162
	s_waitcnt lgkmcnt(2)
	v_mfma_f32_32x32x16_bf16 v[96:111], v[224:227], v[128:131], v[96:111]
	v_mfma_f32_32x32x16_bf16 v[80:95], v[228:231], v[128:131], v[80:95]
	v_add_u32_e32 v228, s15, v169
	ds_read_b128 v[224:227], v228 offset:49152
	ds_read_b128 v[228:231], v228 offset:57344
	v_add_f32_e32 v162, v216, v162
	v_add_f32_e32 v162, v218, v162
	v_add_f32_e32 v162, v220, v162
	v_add_f32_e32 v162, v222, v162
	s_waitcnt lgkmcnt(2)
	v_mfma_f32_32x32x16_bf16 v[96:111], v[246:249], v[124:127], v[96:111]
	v_mfma_f32_32x32x16_bf16 v[80:95], v[238:241], v[124:127], v[80:95]
	v_add_u32_e32 v238, s15, v167
	ds_read_b128 v[246:249], v238 offset:49152
	ds_read_b128 v[238:241], v238 offset:57344
	s_mov_b32 m0, s87
	s_nop 0
	global_load_lds_dwordx4 v150, s[84:85]
	v_add_f32_e32 v162, v168, v162
	v_add_f32_e32 v162, v156, v162
	v_add_f32_e32 v162, v158, v162
	v_add_f32_e32 v162, v166, v162
	s_waitcnt lgkmcnt(2)
	v_mfma_f32_32x32x16_bf16 v[96:111], v[224:227], v[120:123], v[96:111]
	v_mfma_f32_32x32x16_bf16 v[80:95], v[228:231], v[120:123], v[80:95]
	v_add_u32_e32 v228, s15, v159
	ds_read_b128 v[224:227], v228 offset:49152
	ds_read_b128 v[228:231], v228 offset:57344
	v_add_f32_e32 v162, v176, v162
	v_add_f32_e32 v162, v178, v162
	v_add_f32_e32 v162, v180, v162
	v_add_f32_e32 v162, v182, v162
	s_waitcnt lgkmcnt(2)
	v_mfma_f32_32x32x16_bf16 v[96:111], v[246:249], v[116:119], v[96:111]
	v_mfma_f32_32x32x16_bf16 v[80:95], v[238:241], v[116:119], v[80:95]
	s_add_i32 m0, s87, 0x400
	s_nop 0
	global_load_lds_dwordx4 v148, s[84:85]
	s_add_u32 s84, s84, 0x8000
	s_addc_u32 s85, s85, 0
	v_add_f32_e32 v162, v198, v162
	v_add_f32_e32 v162, v196, v162
	v_add_f32_e32 v162, v192, v162
	s_waitcnt lgkmcnt(0)
	v_mfma_f32_32x32x16_bf16 v[96:111], v[224:227], v[112:115], v[96:111]
	v_cvt_pk_bf16_f32 v238, v179, v170
	v_cvt_pk_bf16_f32 v179, v192, v194
	v_add_f32_e32 v162, v194, v162
	v_cvt_pk_bf16_f32 v241, v188, v190
	v_cvt_pk_bf16_f32 v190, v176, v178
	v_cvt_pk_bf16_f32 v178, v198, v196
	v_mfma_f32_32x32x16_bf16 v[80:95], v[228:231], v[112:115], v[80:95]
	s_bitcmp1_b32 s47, 1
	s_cselect_b32 s17, 0, 0x8000
	v_add_u32_e32 v246, s17, v147
	ds_read_b64_tr_b16 v[192:193], v246 offset:0
	ds_read_b64_tr_b16 v[194:195], v246 offset:0x100
	ds_read_b64_tr_b16 v[196:197], v246 offset:0x1000
	ds_read_b64_tr_b16 v[198:199], v246 offset:0x1100
	v_cvt_pk_bf16_f32 v240, v184, v186
	v_cvt_pk_bf16_f32 v184, v206, v200
	ds_read_b64_tr_b16 v[200:201], v246 offset:0x2000
	ds_read_b64_tr_b16 v[202:203], v246 offset:0x2100
	ds_read_b64_tr_b16 v[204:205], v246 offset:0x3000
	ds_read_b64_tr_b16 v[206:207], v246 offset:0x3100
	v_add_f32_e32 v162, v208, v162
	v_cvt_pk_bf16_f32 v180, v208, v210
	ds_read_b64_tr_b16 v[208:209], v246 offset:0x200
	v_add_f32_e32 v162, v210, v162
	ds_read_b64_tr_b16 v[210:211], v246 offset:0x300
	v_add_f32_e32 v162, v212, v162
	ds_read_b64_tr_b16 v[212:213], v246 offset:0x1200
	v_add_f32_e32 v162, v214, v162
	ds_read_b64_tr_b16 v[214:215], v246 offset:0x1300
	v_cvt_pk_bf16_f32 v186, v216, v218
	ds_read_b64_tr_b16 v[216:217], v246 offset:0x2200
	ds_read_b64_tr_b16 v[218:219], v246 offset:0x2300
	ds_read_b64_tr_b16 v[220:221], v246 offset:0x3200
	ds_read_b64_tr_b16 v[222:223], v246 offset:0x3300
	s_waitcnt lgkmcnt(8)
; #define SBAR() __builtin_amdgcn_sched_barrier(0)
; #define PV_RD2(D0, X) const s16x4 X##l0 = tr_read<v_rd_off2(D0, 0, 0)>(vb), X##h0 = tr_read<v_rd_off2(D0, 0, 1)>(vb), X##l1 = tr_read<v_rd_off2(D0, 1, 0)>(vb), X##h1 = tr_read<v_rd_off2(D0, 1, 1)>(vb), \
;                               X##l2 = tr_read<v_rd_off2(D0, 2, 0)>(vb), X##h2 = tr_read<v_rd_off2(D0, 2, 1)>(vb), X##l3 = tr_read<v_rd_off2(D0, 3, 0)>(vb), X##h3 = tr_read<v_rd_off2(D0, 3, 1)>(vb)
; #define EXP4(P, B) do { P[(B) + 0] = __builtin_amdgcn_exp2f(P[(B) + 0]); P[(B) + 1] = __builtin_amdgcn_exp2f(P[(B) + 1]); P[(B) + 2] = __builtin_amdgcn_exp2f(P[(B) + 2]); P[(B) + 3] = __builtin_amdgcn_exp2f(P[(B) + 3]); } while (0)
; #define DWAIT() asm volatile("s_waitcnt vmcnt(0)" ::: "memory")
; #define ROT() do { const int t_ = sP; sP = sC; sC = sN; sN = t_; } while (0)
; __device__ __forceinline__ void pv_d03(f32x16* o, int vb, bf16x8 pa0, bf16x8 pa1, bf16x8 pa2, bf16x8 pa3, f32x16& pn, f32x16& pm) {
;   PV_RD2(0, a);
;   PV_RD2(1, b); asm volatile("s_waitcnt lgkmcnt(8)" ::: "memory"); SBAR(); PV_MM2(o[0], a); EXP4(pn, 0); EXP4(pm, 0); SBAR();
;   PV_RD2(2, c); asm volatile("s_waitcnt lgkmcnt(8)" ::: "memory"); SBAR(); PV_MM2(o[1], b); EXP4(pn, 4); EXP4(pm, 4); SBAR();
;   PV_RD2(3, d); asm volatile("s_waitcnt lgkmcnt(8)" ::: "memory"); SBAR(); PV_MM2(o[2], c); EXP4(pn, 8); EXP4(pm, 8); SBAR();
;   asm volatile("s_waitcnt lgkmcnt(0)" ::: "memory"); SBAR(); PV_MM2(o[3], d); EXP4(pn, 12); EXP4(pm, 12);
; }
; __device__ __forceinline__ void attn_dense_body(const bf16* Qb, const bf16* __restrict__ Kh, const bf16* __restrict__ Vh, const bf16* __restrict__ Zb, ...
;     ...
;     DWAIT(); __syncthreads(); ROT();
;     SDMA(sN, (j + 2) * KVBLK);
;     SBAR(); qkt3(pA0, pA1, KSLOT(sC), qr, r32, hi, cinit);
;     finishSM4<16>(pB0, pB1, l_reg, pa0, pa1, pa2, pa3);
;     pv_d03(o, vb0 + sP * (int)SHM_V, pa0, pa1, pa2, pa3, pA0, pA1);
	v_add_f32_e32 v146, v146, v162
	v_cvt_pk_bf16_f32 v188, v168, v156
	v_cvt_pk_bf16_f32 v239, v172, v174
	s_nop 1
	v_mfma_f32_32x32x16_bf16 v[48:63], v[192:195], v[238:241], v[48:63]
	v_exp_f32_e32 v156, v96
	v_exp_f32_e32 v158, v97
	v_exp_f32_e32 v166, v82
	v_exp_f32_e32 v168, v83
	v_exp_f32_e32 v162, v98
	v_exp_f32_e32 v163, v99
	v_exp_f32_e32 v164, v80
	v_mfma_f32_32x32x16_bf16 v[48:63], v[196:199], v[184:187], v[48:63]
	v_exp_f32_e32 v165, v81
	v_mfma_f32_32x32x16_bf16 v[48:63], v[200:203], v[188:191], v[48:63]
	v_mfma_f32_32x32x16_bf16 v[48:63], v[204:207], v[178:181], v[48:63]
	ds_read_b64_tr_b16 v[80:81], v246 offset:0x400
	ds_read_b64_tr_b16 v[82:83], v246 offset:0x500
	ds_read_b64_tr_b16 v[96:97], v246 offset:0x1400
	ds_read_b64_tr_b16 v[98:99], v246 offset:0x1500
	ds_read_b64_tr_b16 v[192:193], v246 offset:0x2400
	ds_read_b64_tr_b16 v[194:195], v246 offset:0x2500
	ds_read_b64_tr_b16 v[196:197], v246 offset:0x3400
	ds_read_b64_tr_b16 v[198:199], v246 offset:0x3500
	s_waitcnt lgkmcnt(8)
	v_mfma_f32_32x32x16_bf16 v[32:47], v[208:211], v[238:241], v[32:47]
	v_exp_f32_e32 v170, v100
	v_exp_f32_e32 v172, v101
	v_exp_f32_e32 v174, v102
	v_exp_f32_e32 v176, v103
	v_mfma_f32_32x32x16_bf16 v[32:47], v[212:215], v[184:187], v[32:47]
	v_mfma_f32_32x32x16_bf16 v[32:47], v[216:219], v[188:191], v[32:47]
	v_exp_f32_e32 v216, v84
	v_exp_f32_e32 v218, v86
	v_exp_f32_e32 v217, v85
	v_exp_f32_e32 v219, v87
	v_mfma_f32_32x32x16_bf16 v[32:47], v[220:223], v[178:181], v[32:47]
	ds_read_b64_tr_b16 v[84:85], v246 offset:0x600
	ds_read_b64_tr_b16 v[86:87], v246 offset:0x700
	ds_read_b64_tr_b16 v[100:101], v246 offset:0x1600
	ds_read_b64_tr_b16 v[102:103], v246 offset:0x1700
	ds_read_b64_tr_b16 v[200:201], v246 offset:0x2600
	ds_read_b64_tr_b16 v[202:203], v246 offset:0x2700
	ds_read_b64_tr_b16 v[204:205], v246 offset:0x3600
	ds_read_b64_tr_b16 v[206:207], v246 offset:0x3700
	s_waitcnt lgkmcnt(8)
	v_mfma_f32_32x32x16_bf16 v[16:31], v[80:83], v[238:241], v[16:31]
	v_exp_f32_e32 v220, v88
	v_exp_f32_e32 v222, v90
	v_exp_f32_e32 v221, v89
	v_exp_f32_e32 v223, v91
	v_mfma_f32_32x32x16_bf16 v[16:31], v[96:99], v[184:187], v[16:31]
	v_mfma_f32_32x32x16_bf16 v[16:31], v[192:195], v[188:191], v[16:31]
	v_exp_f32_e32 v192, v104
	v_exp_f32_e32 v194, v106
	v_exp_f32_e32 v193, v105
	v_exp_f32_e32 v195, v107
	v_mfma_f32_32x32x16_bf16 v[16:31], v[196:199], v[178:181], v[16:31]
	s_waitcnt lgkmcnt(0)
	s_waitcnt vmcnt(0)
	s_barrier
	s_add_i32 s86, s90, s14
	s_mov_b32 s87, 0x4000
	s_bitcmp1_b32 s47, 1
	s_cselect_b32 s87, 0x18000, s87
	s_add_i32 s87, s87, s90
	v_mfma_f32_32x32x16_bf16 v[0:15], v[84:87], v[238:241], v[0:15]
	v_exp_f32_e32 v196, v94
	v_mfma_f32_32x32x16_bf16 v[0:15], v[100:103], v[184:187], v[0:15]
	v_exp_f32_e32 v186, v108
	v_exp_f32_e32 v187, v109
	v_exp_f32_e32 v197, v95
	v_mfma_f32_32x32x16_bf16 v[0:15], v[200:203], v[188:191], v[0:15]
	v_exp_f32_e32 v188, v110
	v_exp_f32_e32 v190, v92
	v_exp_f32_e32 v189, v111
	v_exp_f32_e32 v191, v93
	v_mfma_f32_32x32x16_bf16 v[0:15], v[204:207], v[178:181], v[0:15]
	s_add_i32 s16, s49, 0
	v_add_u32_e32 v182, s16, v157
	ds_read_b128 v[178:181], v182 offset:49152
	ds_read_b128 v[182:185], v182 offset:57344
	v_add_u32_e32 v246, s16, v177
	ds_read_b128 v[238:241], v246 offset:49152
	ds_read_b128 v[246:249], v246 offset:57344
	s_mov_b32 s17, 0x18000
	s_bitcmp1_b32 s47, 1
	s_cselect_b32 s17, 0x4000, s17
	v_add_u32_e32 v206, s17, v147
	v_cvt_pk_bf16_f32 v214, v186, v187
	v_cvt_pk_bf16_f32 v215, v188, v189
	v_cvt_pk_bf16_f32 v230, v190, v191
	v_cvt_pk_bf16_f32 v212, v192, v193
	s_waitcnt lgkmcnt(2)
	v_mfma_f32_32x32x16_bf16 v[96:111], v[178:181], v[140:143], v[64:79]
	v_mfma_f32_32x32x16_bf16 v[80:95], v[182:185], v[140:143], v[64:79]
	v_add_u32_e32 v182, s16, v175
	ds_read_b128 v[178:181], v182 offset:49152
	ds_read_b128 v[182:185], v182 offset:57344
	s_add_i32 m0, s86, 0xc000
	s_nop 0
	global_load_lds_dwordx4 v154, s[40:41]
	v_cvt_pk_bf16_f32 v213, v194, v195
	v_cvt_pk_bf16_f32 v231, v196, v197
	v_cvt_pk_bf16_f32 v226, v216, v217
	s_waitcnt lgkmcnt(2)
	v_mfma_f32_32x32x16_bf16 v[96:111], v[238:241], v[136:139], v[96:111]
	v_mfma_f32_32x32x16_bf16 v[80:95], v[246:249], v[136:139], v[80:95]
	v_add_u32_e32 v246, s16, v173
	ds_read_b128 v[238:241], v246 offset:49152
	ds_read_b128 v[246:249], v246 offset:57344
	v_cvt_pk_bf16_f32 v227, v218, v219
	v_cvt_pk_bf16_f32 v208, v156, v158
	v_cvt_pk_bf16_f32 v210, v170, v172
	s_waitcnt lgkmcnt(2)
	v_mfma_f32_32x32x16_bf16 v[96:111], v[178:181], v[132:135], v[96:111]
	v_mfma_f32_32x32x16_bf16 v[80:95], v[182:185], v[132:135], v[80:95]
	v_add_u32_e32 v182, s16, v171
	ds_read_b128 v[178:181], v182 offset:49152
	ds_read_b128 v[182:185], v182 offset:57344
	s_add_i32 m0, s86, 0xc400
	s_nop 0
	global_load_lds_dwordx4 v152, s[40:41]
	s_add_u32 s40, s40, 0x8000
	s_addc_u32 s41, s41, 0
	v_cvt_pk_bf16_f32 v209, v162, v163
	v_cvt_pk_bf16_f32 v211, v174, v176
	v_cvt_pk_bf16_f32 v224, v164, v165
	s_waitcnt lgkmcnt(2)
	v_mfma_f32_32x32x16_bf16 v[96:111], v[238:241], v[128:131], v[96:111]
	v_mfma_f32_32x32x16_bf16 v[80:95], v[246:249], v[128:131], v[80:95]
	v_add_u32_e32 v246, s16, v169
	ds_read_b128 v[238:241], v246 offset:49152
	ds_read_b128 v[246:249], v246 offset:57344
	v_cvt_pk_bf16_f32 v225, v166, v168
	v_cvt_pk_bf16_f32 v228, v220, v221
	v_cvt_pk_bf16_f32 v229, v222, v223
	s_waitcnt lgkmcnt(2)
	v_mfma_f32_32x32x16_bf16 v[96:111], v[178:181], v[124:127], v[96:111]
	v_mfma_f32_32x32x16_bf16 v[80:95], v[182:185], v[124:127], v[80:95]
	v_add_u32_e32 v182, s16, v167
	ds_read_b128 v[178:181], v182 offset:49152
	ds_read_b128 v[182:185], v182 offset:57344
	s_mov_b32 m0, s87
	s_nop 0
	global_load_lds_dwordx4 v150, s[84:85]
	s_waitcnt lgkmcnt(2)
; #define SBAR() __builtin_amdgcn_sched_barrier(0)
; #define DWAIT() asm volatile("s_waitcnt vmcnt(0)" ::: "memory")
; #define ROT() do { const int t_ = sP; sP = sC; sC = sN; sN = t_; } while (0)
; __device__ __forceinline__ void qkt3(f32x16& p0, f32x16& p1, const bf16* Ks, const bf16x8* qr, int r32, int hi, const f32x16& cinit) {
;   { int cb = (hi * 8) * 2;
;     bf16x8 b0 = *reinterpret_cast<const bf16x8*>((const char*)Ks + KSWZ(r32, cb));
;     bf16x8 b1 = *reinterpret_cast<const bf16x8*>((const char*)Ks + KSWZ(32 + r32, cb));
;     p0 = __builtin_amdgcn_mfma_f32_32x32x16_bf16(b0, qr[0], cinit, 0, 0, 0);
;     p1 = __builtin_amdgcn_mfma_f32_32x32x16_bf16(b1, qr[0], cinit, 0, 0, 0); }
;   for (int d0 = 1; d0 < 8; ++d0) { int cb = (d0 * 16 + hi * 8) * 2;
;     bf16x8 b0 = *reinterpret_cast<const bf16x8*>((const char*)Ks + KSWZ(r32, cb));
;     bf16x8 b1 = *reinterpret_cast<const bf16x8*>((const char*)Ks + KSWZ(32 + r32, cb));
;     p0 = __builtin_amdgcn_mfma_f32_32x32x16_bf16(b0, qr[d0], p0, 0, 0, 0);
;     p1 = __builtin_amdgcn_mfma_f32_32x32x16_bf16(b1, qr[d0], p1, 0, 0, 0); }
; }
; __device__ __forceinline__ void attn_dense_body(const bf16* Qb, const bf16* __restrict__ Kh, const bf16* __restrict__ Vh, const bf16* __restrict__ Zb, ...
;     ...
;   for (int j = 1; j + 1 < NT; j += 2) {
;     SDMA(sN, (j + 1) * KVBLK);
;     SBAR(); qkt3(pB0, pB1, KSLOT(sC), qr, r32, hi, cinit);
;     finishSM4<16>(pA0, pA1, l_reg, pa0, pa1, pa2, pa3);
;     pv_d03(o, vb0 + sP * (int)SHM_V, pa0, pa1, pa2, pa3, pB0, pB1);
;     DWAIT(); __syncthreads(); ROT();
;     SDMA(sN, (j + 2) * KVBLK);
;     SBAR(); qkt3(pA0, pA1, KSLOT(sC), qr, r32, hi, cinit);
;     finishSM4<16>(pB0, pB1, l_reg, pa0, pa1, pa2, pa3);
;     pv_d03(o, vb0 + sP * (int)SHM_V, pa0, pa1, pa2, pa3, pA0, pA1);
;     DWAIT(); __syncthreads(); ROT();
	v_mfma_f32_32x32x16_bf16 v[96:111], v[238:241], v[120:123], v[96:111]
	v_mfma_f32_32x32x16_bf16 v[80:95], v[246:249], v[120:123], v[80:95]
	v_add_u32_e32 v246, s16, v159
	ds_read_b128 v[238:241], v246 offset:49152
	ds_read_b128 v[246:249], v246 offset:57344
	s_waitcnt lgkmcnt(2)
	v_mfma_f32_32x32x16_bf16 v[96:111], v[178:181], v[116:119], v[96:111]
	v_mfma_f32_32x32x16_bf16 v[80:95], v[182:185], v[116:119], v[80:95]
	s_add_i32 m0, s87, 0x400
	s_nop 0
	global_load_lds_dwordx4 v148, s[84:85]
	s_add_u32 s84, s84, 0x8000
	s_addc_u32 s85, s85, 0
	v_add_f32_e32 v178, 0, v156
	v_add_f32_e32 v178, v158, v178
	v_add_f32_e32 v178, v162, v178
	v_add_f32_e32 v178, v163, v178
	v_add_f32_e32 v178, v170, v178
	v_add_f32_e32 v178, v172, v178
	v_add_f32_e32 v178, v174, v178
	v_add_f32_e32 v178, v176, v178
	v_add_f32_e32 v178, v192, v178
	v_add_f32_e32 v178, v193, v178
	v_add_f32_e32 v178, v194, v178
	v_add_f32_e32 v178, v195, v178
	v_add_f32_e32 v178, v186, v178
	v_add_f32_e32 v178, v187, v178
	v_add_f32_e32 v178, v188, v178
	v_add_f32_e32 v178, v189, v178
	s_waitcnt lgkmcnt(0)
	v_mfma_f32_32x32x16_bf16 v[96:111], v[238:241], v[112:115], v[96:111]
	v_add_f32_e32 v178, v164, v178
	v_add_f32_e32 v178, v165, v178
	v_add_f32_e32 v178, v166, v178
	v_add_f32_e32 v178, v168, v178
	v_add_f32_e32 v178, v216, v178
	v_add_f32_e32 v178, v217, v178
	v_add_f32_e32 v178, v218, v178
	v_add_f32_e32 v178, v219, v178
	v_add_f32_e32 v178, v220, v178
	v_add_f32_e32 v178, v221, v178
	v_add_f32_e32 v178, v222, v178
	v_add_f32_e32 v178, v223, v178
	v_add_f32_e32 v178, v190, v178
	v_add_f32_e32 v178, v191, v178
	v_add_f32_e32 v178, v196, v178
	v_add_f32_e32 v178, v197, v178
	v_add_f32_e32 v146, v146, v178
	ds_read_b64_tr_b16 v[178:179], v206 offset:0
	ds_read_b64_tr_b16 v[180:181], v206 offset:0x100
	v_mfma_f32_32x32x16_bf16 v[80:95], v[246:249], v[112:115], v[80:95]
	ds_read_b64_tr_b16 v[182:183], v206 offset:0x1000
	ds_read_b64_tr_b16 v[184:185], v206 offset:0x1100
	ds_read_b64_tr_b16 v[186:187], v206 offset:0x2000
	ds_read_b64_tr_b16 v[188:189], v206 offset:0x2100
	ds_read_b64_tr_b16 v[190:191], v206 offset:0x3000
	ds_read_b64_tr_b16 v[192:193], v206 offset:0x3100
	ds_read_b64_tr_b16 v[194:195], v206 offset:0x200
	ds_read_b64_tr_b16 v[196:197], v206 offset:0x300
	ds_read_b64_tr_b16 v[198:199], v206 offset:0x1200
	ds_read_b64_tr_b16 v[200:201], v206 offset:0x1300
	ds_read_b64_tr_b16 v[202:203], v206 offset:0x2200
	ds_read_b64_tr_b16 v[204:205], v206 offset:0x2300
	ds_read_b64_tr_b16 v[216:217], v206 offset:0x3200
	ds_read_b64_tr_b16 v[218:219], v206 offset:0x3300
	s_waitcnt lgkmcnt(8)
	v_mfma_f32_32x32x16_bf16 v[48:63], v[178:181], v[208:211], v[48:63]
	v_exp_f32_e32 v179, v96
	v_exp_f32_e32 v170, v97
	v_exp_f32_e32 v172, v98
	v_exp_f32_e32 v174, v99
	s_nop 6
	v_exp_f32_e32 v168, v80
	v_exp_f32_e32 v156, v81
	v_exp_f32_e32 v158, v82
	v_mfma_f32_32x32x16_bf16 v[48:63], v[182:185], v[212:215], v[48:63]
	v_exp_f32_e32 v166, v83
	v_mfma_f32_32x32x16_bf16 v[48:63], v[186:189], v[224:227], v[48:63]
	v_mfma_f32_32x32x16_bf16 v[48:63], v[190:193], v[228:231], v[48:63]
	ds_read_b64_tr_b16 v[80:81], v206 offset:0x400
	ds_read_b64_tr_b16 v[82:83], v206 offset:0x500
	ds_read_b64_tr_b16 v[96:97], v206 offset:0x1400
	ds_read_b64_tr_b16 v[98:99], v206 offset:0x1500
	ds_read_b64_tr_b16 v[220:221], v206 offset:0x2400
	ds_read_b64_tr_b16 v[222:223], v206 offset:0x2500
	ds_read_b64_tr_b16 v[238:239], v206 offset:0x3400
	ds_read_b64_tr_b16 v[240:241], v206 offset:0x3500
	s_waitcnt lgkmcnt(8)
	v_mfma_f32_32x32x16_bf16 v[32:47], v[194:197], v[208:211], v[32:47]
	v_exp_f32_e32 v184, v100
	v_exp_f32_e32 v186, v101
	v_exp_f32_e32 v188, v102
	v_exp_f32_e32 v190, v103
	v_exp_f32_e32 v176, v84
	v_exp_f32_e32 v178, v85
	v_exp_f32_e32 v180, v86
	v_mfma_f32_32x32x16_bf16 v[32:47], v[198:201], v[212:215], v[32:47]
	v_exp_f32_e32 v182, v87
	v_mfma_f32_32x32x16_bf16 v[32:47], v[202:205], v[224:227], v[32:47]
	v_mfma_f32_32x32x16_bf16 v[32:47], v[216:219], v[228:231], v[32:47]
	ds_read_b64_tr_b16 v[84:85], v206 offset:0x600
	ds_read_b64_tr_b16 v[86:87], v206 offset:0x700
	ds_read_b64_tr_b16 v[100:101], v206 offset:0x1600
	ds_read_b64_tr_b16 v[102:103], v206 offset:0x1700
	ds_read_b64_tr_b16 v[248:249], v206 offset:0x2600
	ds_read_b64_tr_b16 v[250:251], v206 offset:0x2700
	ds_read_b64_tr_b16 v[162:163], v206 offset:0x3600
	ds_read_b64_tr_b16 v[164:165], v206 offset:0x3700
	s_waitcnt lgkmcnt(8)
	v_mfma_f32_32x32x16_bf16 v[16:31], v[80:83], v[208:211], v[16:31]
	v_exp_f32_e32 v206, v104
	v_exp_f32_e32 v200, v105
	v_exp_f32_e32 v202, v106
	v_exp_f32_e32 v204, v107
	v_exp_f32_e32 v198, v88
	v_exp_f32_e32 v196, v89
	v_exp_f32_e32 v192, v90
	v_mfma_f32_32x32x16_bf16 v[16:31], v[96:99], v[212:215], v[16:31]
	v_exp_f32_e32 v194, v91
	v_mfma_f32_32x32x16_bf16 v[16:31], v[220:223], v[224:227], v[16:31]
	v_mfma_f32_32x32x16_bf16 v[16:31], v[238:241], v[228:231], v[16:31]
	s_waitcnt lgkmcnt(0)
	v_mfma_f32_32x32x16_bf16 v[0:15], v[84:87], v[208:211], v[0:15]
	v_exp_f32_e32 v216, v108
	v_exp_f32_e32 v218, v109
	v_exp_f32_e32 v220, v110
	v_exp_f32_e32 v222, v111
	v_exp_f32_e32 v208, v92
	v_exp_f32_e32 v210, v93
	v_mfma_f32_32x32x16_bf16 v[0:15], v[100:103], v[212:215], v[0:15]
	v_exp_f32_e32 v212, v94
	v_exp_f32_e32 v214, v95
	s_add_i32 s47, s47, 2
	s_mov_b32 s54, s48
	s_mov_b32 s48, s53
	v_mfma_f32_32x32x16_bf16 v[0:15], v[248:251], v[224:227], v[0:15]
	s_waitcnt vmcnt(0)
	s_barrier
	s_cmp_lt_u32 s47, s52
	v_mfma_f32_32x32x16_bf16 v[0:15], v[162:165], v[228:231], v[0:15]
	s_cbranch_scc1 .LBB0_117
; #define SBAR() __builtin_amdgcn_sched_barrier(0)
; #define PV_RD2(D0, X) const s16x4 X##l0 = tr_read<v_rd_off2(D0, 0, 0)>(vb), X##h0 = tr_read<v_rd_off2(D0, 0, 1)>(vb), X##l1 = tr_read<v_rd_off2(D0, 1, 0)>(vb), X##h1 = tr_read<v_rd_off2(D0, 1, 1)>(vb), \
;                               X##l2 = tr_read<v_rd_off2(D0, 2, 0)>(vb), X##h2 = tr_read<v_rd_off2(D0, 2, 1)>(vb), X##l3 = tr_read<v_rd_off2(D0, 3, 0)>(vb), X##h3 = tr_read<v_rd_off2(D0, 3, 1)>(vb)
; #define EXP4(P, B) do { P[(B) + 0] = __builtin_amdgcn_exp2f(P[(B) + 0]); P[(B) + 1] = __builtin_amdgcn_exp2f(P[(B) + 1]); P[(B) + 2] = __builtin_amdgcn_exp2f(P[(B) + 2]); P[(B) + 3] = __builtin_amdgcn_exp2f(P[(B) + 3]); } while (0)
; __device__ __forceinline__ void qkt3(f32x16& p0, f32x16& p1, const bf16* Ks, const bf16x8* qr, int r32, int hi, const f32x16& cinit) {
;   { int cb = (hi * 8) * 2;
;     bf16x8 b0 = *reinterpret_cast<const bf16x8*>((const char*)Ks + KSWZ(r32, cb));
;     bf16x8 b1 = *reinterpret_cast<const bf16x8*>((const char*)Ks + KSWZ(32 + r32, cb));
;     p0 = __builtin_amdgcn_mfma_f32_32x32x16_bf16(b0, qr[0], cinit, 0, 0, 0);
;     p1 = __builtin_amdgcn_mfma_f32_32x32x16_bf16(b1, qr[0], cinit, 0, 0, 0); }
;   for (int d0 = 1; d0 < 8; ++d0) { int cb = (d0 * 16 + hi * 8) * 2;
;     bf16x8 b0 = *reinterpret_cast<const bf16x8*>((const char*)Ks + KSWZ(r32, cb));
;     bf16x8 b1 = *reinterpret_cast<const bf16x8*>((const char*)Ks + KSWZ(32 + r32, cb));
;     p0 = __builtin_amdgcn_mfma_f32_32x32x16_bf16(b0, qr[d0], p0, 0, 0, 0);
;     p1 = __builtin_amdgcn_mfma_f32_32x32x16_bf16(b1, qr[d0], p1, 0, 0, 0); }
; }
; __device__ __forceinline__ void pv_d03(f32x16* o, int vb, bf16x8 pa0, bf16x8 pa1, bf16x8 pa2, bf16x8 pa3, f32x16& pn, f32x16& pm) {
;   PV_RD2(0, a);
;   PV_RD2(1, b); asm volatile("s_waitcnt lgkmcnt(8)" ::: "memory"); SBAR(); PV_MM2(o[0], a); EXP4(pn, 0); EXP4(pm, 0); SBAR();
;   PV_RD2(2, c); asm volatile("s_waitcnt lgkmcnt(8)" ::: "memory"); SBAR(); PV_MM2(o[1], b); EXP4(pn, 4); EXP4(pm, 4); SBAR();
;   PV_RD2(3, d); asm volatile("s_waitcnt lgkmcnt(8)" ::: "memory"); SBAR(); PV_MM2(o[2], c); EXP4(pn, 8); EXP4(pm, 8); SBAR();
;   asm volatile("s_waitcnt lgkmcnt(0)" ::: "memory"); SBAR(); PV_MM2(o[3], d); EXP4(pn, 12); EXP4(pm, 12);
; }
	s_add_u32 s40, s36, s44
	s_addc_u32 s41, s50, s45
	s_add_i32 s14, s14, 0
	v_add_u32_e32 v100, s14, v157
	ds_read_b128 v[96:99], v100 offset:49152
	v_add_u32_e32 v104, s14, v159
	v_add_f32_e32 v148, 0, v179
	v_cvt_pk_bf16_f32 v108, v179, v170
	v_cvt_pk_bf16_f32 v109, v172, v174
	v_cvt_pk_bf16_f32 v110, v184, v186
	v_cvt_pk_bf16_f32 v111, v188, v190
	s_waitcnt lgkmcnt(0)
	v_mfma_f32_32x32x16_bf16 v[80:95], v[96:99], v[140:143], v[64:79]
	ds_read_b128 v[96:99], v100 offset:57344
	v_add_u32_e32 v100, s14, v177
	s_waitcnt lgkmcnt(0)
	v_mfma_f32_32x32x16_bf16 v[64:79], v[96:99], v[140:143], v[64:79]
	ds_read_b128 v[96:99], v100 offset:49152
	s_waitcnt lgkmcnt(0)
	v_mfma_f32_32x32x16_bf16 v[80:95], v[96:99], v[136:139], v[80:95]
	ds_read_b128 v[96:99], v100 offset:57344
	v_add_u32_e32 v100, s14, v175
	s_waitcnt lgkmcnt(0)
	v_mfma_f32_32x32x16_bf16 v[64:79], v[96:99], v[136:139], v[64:79]
	ds_read_b128 v[96:99], v100 offset:49152
	s_waitcnt lgkmcnt(0)
	v_mfma_f32_32x32x16_bf16 v[80:95], v[96:99], v[132:135], v[80:95]
	ds_read_b128 v[96:99], v100 offset:57344
	v_add_u32_e32 v100, s14, v173
	s_waitcnt lgkmcnt(0)
	v_mfma_f32_32x32x16_bf16 v[64:79], v[96:99], v[132:135], v[64:79]
	ds_read_b128 v[96:99], v100 offset:49152
	s_waitcnt lgkmcnt(0)
	v_mfma_f32_32x32x16_bf16 v[80:95], v[96:99], v[128:131], v[80:95]
	ds_read_b128 v[96:99], v100 offset:57344
	v_add_u32_e32 v100, s14, v171
	s_waitcnt lgkmcnt(0)
	v_mfma_f32_32x32x16_bf16 v[64:79], v[96:99], v[128:131], v[64:79]
	ds_read_b128 v[96:99], v100 offset:49152
	s_waitcnt lgkmcnt(0)
	v_mfma_f32_32x32x16_bf16 v[80:95], v[96:99], v[124:127], v[80:95]
	ds_read_b128 v[96:99], v100 offset:57344
	v_add_u32_e32 v100, s14, v169
	s_waitcnt lgkmcnt(0)
	v_mfma_f32_32x32x16_bf16 v[64:79], v[96:99], v[124:127], v[64:79]
	ds_read_b128 v[96:99], v100 offset:49152
	s_waitcnt lgkmcnt(0)
	v_mfma_f32_32x32x16_bf16 v[80:95], v[96:99], v[120:123], v[80:95]
	ds_read_b128 v[96:99], v100 offset:57344
	v_add_u32_e32 v100, s14, v167
	s_waitcnt lgkmcnt(0)
	v_mfma_f32_32x32x16_bf16 v[64:79], v[96:99], v[120:123], v[64:79]
	ds_read_b128 v[96:99], v100 offset:49152
	s_waitcnt lgkmcnt(0)
	v_mfma_f32_32x32x16_bf16 v[80:95], v[96:99], v[116:119], v[80:95]
	ds_read_b128 v[96:99], v100 offset:57344
	ds_read_b128 v[100:103], v104 offset:49152
	ds_read_b128 v[104:107], v104 offset:57344
	s_waitcnt lgkmcnt(2)
	v_mfma_f32_32x32x16_bf16 v[64:79], v[96:99], v[116:119], v[64:79]
	v_cvt_pk_bf16_f32 v96, v206, v200
	v_cvt_pk_bf16_f32 v97, v202, v204
	v_cvt_pk_bf16_f32 v98, v216, v218
	v_cvt_pk_bf16_f32 v99, v220, v222
	v_cvt_pk_bf16_f32 v116, v198, v196
	v_cvt_pk_bf16_f32 v117, v192, v194
	v_cvt_pk_bf16_f32 v118, v208, v210
	s_waitcnt lgkmcnt(1)
	v_mfma_f32_32x32x16_bf16 v[80:95], v[100:103], v[112:115], v[80:95]
	v_cvt_pk_bf16_f32 v100, v168, v156
	v_cvt_pk_bf16_f32 v101, v158, v166
	v_cvt_pk_bf16_f32 v102, v176, v178
	v_cvt_pk_bf16_f32 v103, v180, v182
	v_cvt_pk_bf16_f32 v119, v212, v214
	s_waitcnt lgkmcnt(0)
	v_mfma_f32_32x32x16_bf16 v[64:79], v[104:107], v[112:115], v[64:79]
	s_mov_b32 s87, 0x18000
	s_bitcmp1_b32 s52, 1
	s_cselect_b32 s87, 0x4000, s87
	v_add_u32_e32 v246, s87, v147
	s_bitcmp1_b32 s52, 1
	s_cselect_b32 s87, 0, 0x8000
	v_add_u32_e32 v147, s87, v147
	ds_read_b64_tr_b16 v[104:105], v147 offset:0
	ds_read_b64_tr_b16 v[106:107], v147 offset:0x100
	ds_read_b64_tr_b16 v[112:113], v147 offset:0x1000
	ds_read_b64_tr_b16 v[114:115], v147 offset:0x1100
	ds_read_b64_tr_b16 v[120:121], v147 offset:0x2000
	ds_read_b64_tr_b16 v[122:123], v147 offset:0x2100
	ds_read_b64_tr_b16 v[124:125], v147 offset:0x3000
	ds_read_b64_tr_b16 v[126:127], v147 offset:0x3100
	ds_read_b64_tr_b16 v[128:129], v147 offset:0x200
	ds_read_b64_tr_b16 v[130:131], v147 offset:0x300
	ds_read_b64_tr_b16 v[132:133], v147 offset:0x1200
	ds_read_b64_tr_b16 v[134:135], v147 offset:0x1300
	ds_read_b64_tr_b16 v[136:137], v147 offset:0x2200
	ds_read_b64_tr_b16 v[138:139], v147 offset:0x2300
	ds_read_b64_tr_b16 v[140:141], v147 offset:0x3200
	ds_read_b64_tr_b16 v[142:143], v147 offset:0x3300
	s_waitcnt lgkmcnt(8)
	s_nop 0
	v_mfma_f32_32x32x16_bf16 v[48:63], v[104:107], v[108:111], v[48:63]
	s_nop 1
	v_exp_f32_e32 v171, v80
	v_exp_f32_e32 v173, v81
	v_exp_f32_e32 v175, v82
	v_exp_f32_e32 v185, v83
	s_nop 2
	v_exp_f32_e32 v157, v64
	v_exp_f32_e32 v159, v65
	v_exp_f32_e32 v167, v66
	v_mfma_f32_32x32x16_bf16 v[48:63], v[112:115], v[96:99], v[48:63]
	v_exp_f32_e32 v177, v67
	v_mfma_f32_32x32x16_bf16 v[48:63], v[120:123], v[100:103], v[48:63]
	v_mfma_f32_32x32x16_bf16 v[48:63], v[124:127], v[116:119], v[48:63]
	ds_read_b64_tr_b16 v[64:65], v147 offset:0x400
	ds_read_b64_tr_b16 v[66:67], v147 offset:0x500
	ds_read_b64_tr_b16 v[80:81], v147 offset:0x1400
	ds_read_b64_tr_b16 v[82:83], v147 offset:0x1500
	ds_read_b64_tr_b16 v[104:105], v147 offset:0x2400
	ds_read_b64_tr_b16 v[106:107], v147 offset:0x2500
	ds_read_b64_tr_b16 v[112:113], v147 offset:0x3400
	ds_read_b64_tr_b16 v[114:115], v147 offset:0x3500
	s_waitcnt lgkmcnt(8)
	v_mfma_f32_32x32x16_bf16 v[32:47], v[128:131], v[108:111], v[32:47]
	v_exp_f32_e32 v187, v84
	v_exp_f32_e32 v189, v85
	v_exp_f32_e32 v191, v86
	v_exp_f32_e32 v207, v87
	v_exp_f32_e32 v179, v68
	v_exp_f32_e32 v181, v69
	v_exp_f32_e32 v183, v70
	v_mfma_f32_32x32x16_bf16 v[32:47], v[132:135], v[96:99], v[32:47]
	v_exp_f32_e32 v199, v71
	v_mfma_f32_32x32x16_bf16 v[32:47], v[136:139], v[100:103], v[32:47]
	v_mfma_f32_32x32x16_bf16 v[32:47], v[140:143], v[116:119], v[32:47]
	ds_read_b64_tr_b16 v[68:69], v147 offset:0x600
	ds_read_b64_tr_b16 v[70:71], v147 offset:0x700
	ds_read_b64_tr_b16 v[84:85], v147 offset:0x1600
	ds_read_b64_tr_b16 v[86:87], v147 offset:0x1700
	ds_read_b64_tr_b16 v[120:121], v147 offset:0x2600
	ds_read_b64_tr_b16 v[122:123], v147 offset:0x2700
	ds_read_b64_tr_b16 v[124:125], v147 offset:0x3600
	ds_read_b64_tr_b16 v[126:127], v147 offset:0x3700
	s_waitcnt lgkmcnt(8)
; #define SBAR() __builtin_amdgcn_sched_barrier(0)
; #define PK8(P, BASE, OUT) do { u32x4 w = {cvtpk(P[BASE + 0], P[BASE + 1]), cvtpk(P[BASE + 2], P[BASE + 3]), cvtpk(P[BASE + 4], P[BASE + 5]), cvtpk(P[BASE + 6], P[BASE + 7])}; OUT = *reinterpret_cast<bf16x8*>(&w); } while (0)
; #define PV_RD2(D0, X) const s16x4 X##l0 = tr_read<v_rd_off2(D0, 0, 0)>(vb), X##h0 = tr_read<v_rd_off2(D0, 0, 1)>(vb), X##l1 = tr_read<v_rd_off2(D0, 1, 0)>(vb), X##h1 = tr_read<v_rd_off2(D0, 1, 1)>(vb), \
;                               X##l2 = tr_read<v_rd_off2(D0, 2, 0)>(vb), X##h2 = tr_read<v_rd_off2(D0, 2, 1)>(vb), X##l3 = tr_read<v_rd_off2(D0, 3, 0)>(vb), X##h3 = tr_read<v_rd_off2(D0, 3, 1)>(vb)
; template <int FIRST> __device__ __forceinline__ void finishSM4(f32x16& p0, f32x16& p1, float& l_reg, bf16x8& pa0, bf16x8& pa1, bf16x8& pa2, bf16x8& pa3) {
;   for (int r = FIRST; r < 16; ++r) p1[r] = __builtin_amdgcn_exp2f(p1[r]);
;   float ps = 0; for (int r = 0; r < 16; ++r) ps += p0[r]; for (int r = 0; r < 16; ++r) ps += p1[r];
;   l_reg += ps;
;     ...
;   PK8(p0, 0, pa0); PK8(p0, 8, pa1); PK8(p1, 0, pa2); PK8(p1, 8, pa3);
;     ...
; }
; __device__ __forceinline__ void pv_d02(f32x16* o, int vb, bf16x8 pa0, bf16x8 pa1, bf16x8 pa2, bf16x8 pa3) {
;   PV_RD2(0, a);
;   PV_RD2(1, b); asm volatile("s_waitcnt lgkmcnt(8)" ::: "memory"); SBAR(); PV_MM2(o[0], a); SBAR();
;   PV_RD2(2, c); asm volatile("s_waitcnt lgkmcnt(8)" ::: "memory"); SBAR(); PV_MM2(o[1], b); SBAR();
;   PV_RD2(3, d); asm volatile("s_waitcnt lgkmcnt(8)" ::: "memory"); SBAR(); PV_MM2(o[2], c); SBAR();
;   asm volatile("s_waitcnt lgkmcnt(0)" ::: "memory"); SBAR(); PV_MM2(o[3], d);
; }
	v_mfma_f32_32x32x16_bf16 v[16:31], v[64:67], v[108:111], v[16:31]
	v_exp_f32_e32 v201, v88
	v_exp_f32_e32 v203, v89
	v_exp_f32_e32 v205, v90
	v_exp_f32_e32 v217, v91
	v_exp_f32_e32 v197, v72
	v_exp_f32_e32 v193, v73
	v_exp_f32_e32 v195, v74
	v_mfma_f32_32x32x16_bf16 v[16:31], v[80:83], v[96:99], v[16:31]
	v_exp_f32_e32 v209, v75
	v_mfma_f32_32x32x16_bf16 v[16:31], v[104:107], v[100:103], v[16:31]
	v_mfma_f32_32x32x16_bf16 v[16:31], v[112:115], v[116:119], v[16:31]
	s_waitcnt lgkmcnt(0)
	v_mov_b32_e32 v149, v161
	v_add_f32_e64 v64, v170, v148
	v_add_f32_e64 v65, v171, v149
	v_mfma_f32_32x32x16_bf16 v[0:15], v[68:71], v[108:111], v[0:15]
	v_add_f32_e64 v64, v172, v64
	v_add_f32_e64 v65, v173, v65
	v_exp_f32_e32 v219, v92
	v_pk_add_f32 v[64:65], v[174:175], v[64:65]
	v_exp_f32_e32 v221, v93
	v_pk_add_f32 v[64:65], v[184:185], v[64:65]
	v_exp_f32_e32 v223, v94
	v_pk_add_f32 v[64:65], v[186:187], v[64:65]
	v_exp_f32_e32 v169, v95
	v_pk_add_f32 v[64:65], v[188:189], v[64:65]
	v_mfma_f32_32x32x16_bf16 v[0:15], v[84:87], v[96:99], v[0:15]
	v_add_f32_e64 v64, v190, v64
	v_add_f32_e64 v65, v191, v65
	v_exp_f32_e32 v211, v76
	v_pk_add_f32 v[64:65], v[206:207], v[64:65]
	v_exp_f32_e32 v213, v77
	v_pk_add_f32 v[64:65], v[200:201], v[64:65]
	v_exp_f32_e32 v215, v78
	v_pk_add_f32 v[64:65], v[202:203], v[64:65]
	v_mfma_f32_32x32x16_bf16 v[0:15], v[120:123], v[100:103], v[0:15]
	v_add_f32_e64 v64, v204, v64
	v_add_f32_e64 v65, v205, v65
	v_exp_f32_e32 v147, v79
	v_pk_add_f32 v[64:65], v[216:217], v[64:65]
	v_cvt_pk_bf16_f32 v66, v187, v189
	v_pk_add_f32 v[64:65], v[218:219], v[64:65]
	v_cvt_pk_bf16_f32 v67, v191, v207
	v_pk_add_f32 v[64:65], v[220:221], v[64:65]
	v_mfma_f32_32x32x16_bf16 v[0:15], v[124:127], v[116:119], v[0:15]
	v_add_f32_e64 v64, v222, v64
	v_add_f32_e64 v65, v223, v65
	v_cvt_pk_bf16_f32 v68, v201, v203
	v_add_f32_e64 v64, v168, v64
	v_add_f32_e64 v65, v169, v65
	v_cvt_pk_bf16_f32 v69, v205, v217
	v_pk_add_f32 v[64:65], v[156:157], v[64:65]
	v_cvt_pk_bf16_f32 v70, v219, v221
	v_pk_add_f32 v[64:65], v[158:159], v[64:65]
	v_cvt_pk_bf16_f32 v71, v223, v169
	v_pk_add_f32 v[64:65], v[166:167], v[64:65]
	v_cvt_pk_bf16_f32 v72, v157, v159
	v_pk_add_f32 v[64:65], v[176:177], v[64:65]
	v_cvt_pk_bf16_f32 v73, v167, v177
	v_pk_add_f32 v[64:65], v[178:179], v[64:65]
	v_cvt_pk_bf16_f32 v74, v179, v181
	v_pk_add_f32 v[64:65], v[180:181], v[64:65]
	v_cvt_pk_bf16_f32 v75, v183, v199
	v_pk_add_f32 v[64:65], v[182:183], v[64:65]
	v_cvt_pk_bf16_f32 v76, v197, v193
	v_pk_add_f32 v[64:65], v[198:199], v[64:65]
	v_cvt_pk_bf16_f32 v77, v195, v209
	v_pk_add_f32 v[64:65], v[196:197], v[64:65]
	v_cvt_pk_bf16_f32 v78, v211, v213
	v_pk_add_f32 v[64:65], v[192:193], v[64:65]
	v_cvt_pk_bf16_f32 v79, v215, v147
	v_pk_add_f32 v[64:65], v[194:195], v[64:65]
	s_nop 0
	v_pk_add_f32 v[64:65], v[208:209], v[64:65]
	s_nop 0
	v_pk_add_f32 v[64:65], v[210:211], v[64:65]
	s_nop 0
	v_pk_add_f32 v[64:65], v[212:213], v[64:65]
	s_nop 0
	v_pk_add_f32 v[64:65], v[214:215], v[64:65]
	s_nop 0
	v_pk_add_f32 v[64:65], v[146:147], v[64:65]
	s_nop 0
	v_pk_add_f32 v[112:113], v[64:65], v[64:65] op_sel:[0,1] op_sel_hi:[1,0]
	v_cvt_pk_bf16_f32 v64, v171, v173
	v_cvt_pk_bf16_f32 v65, v175, v185
	v_lshlrev_b32_e32 v222, 2, v245
	v_lshl_add_u32 v222, v160, 10, v222
	v_ashrrev_i32_e32 v223, 31, v222
	v_lshlrev_b64 v[222:223], 1, v[222:223]
	v_lshl_add_u64 v[220:221], s[40:41], 0, v[222:223]
	global_load_dwordx2 v[162:163], v[220:221], off
	global_load_dwordx2 v[164:165], v[220:221], off offset:16
	global_load_dwordx2 v[166:167], v[220:221], off offset:32
	global_load_dwordx2 v[168:169], v[220:221], off offset:48
	global_load_dwordx2 v[170:171], v[220:221], off offset:64
	global_load_dwordx2 v[172:173], v[220:221], off offset:80
	global_load_dwordx2 v[174:175], v[220:221], off offset:96
	global_load_dwordx2 v[176:177], v[220:221], off offset:112
	global_load_dwordx2 v[178:179], v[220:221], off offset:128
	global_load_dwordx2 v[180:181], v[220:221], off offset:144
	global_load_dwordx2 v[182:183], v[220:221], off offset:160
	global_load_dwordx2 v[184:185], v[220:221], off offset:176
	global_load_dwordx2 v[186:187], v[220:221], off offset:192
	global_load_dwordx2 v[188:189], v[220:221], off offset:208
	global_load_dwordx2 v[190:191], v[220:221], off offset:224
	global_load_dwordx2 v[192:193], v[220:221], off offset:240
	ds_read_b64_tr_b16 v[80:81], v246 offset:0
	ds_read_b64_tr_b16 v[82:83], v246 offset:0x100
	ds_read_b64_tr_b16 v[84:85], v246 offset:0x1000
	ds_read_b64_tr_b16 v[86:87], v246 offset:0x1100
	ds_read_b64_tr_b16 v[88:89], v246 offset:0x2000
	ds_read_b64_tr_b16 v[90:91], v246 offset:0x2100
	ds_read_b64_tr_b16 v[92:93], v246 offset:0x3000
	ds_read_b64_tr_b16 v[94:95], v246 offset:0x3100
	ds_read_b64_tr_b16 v[96:97], v246 offset:0x200
	ds_read_b64_tr_b16 v[98:99], v246 offset:0x300
	ds_read_b64_tr_b16 v[100:101], v246 offset:0x1200
	ds_read_b64_tr_b16 v[102:103], v246 offset:0x1300
	ds_read_b64_tr_b16 v[104:105], v246 offset:0x2200
	ds_read_b64_tr_b16 v[106:107], v246 offset:0x2300
	ds_read_b64_tr_b16 v[108:109], v246 offset:0x3200
	ds_read_b64_tr_b16 v[110:111], v246 offset:0x3300
	s_waitcnt lgkmcnt(8)
	s_nop 1
	v_mfma_f32_32x32x16_bf16 v[48:63], v[80:83], v[64:67], v[48:63]
	v_mfma_f32_32x32x16_bf16 v[48:63], v[84:87], v[68:71], v[48:63]
	v_mfma_f32_32x32x16_bf16 v[48:63], v[88:91], v[72:75], v[48:63]
	v_mfma_f32_32x32x16_bf16 v[48:63], v[92:95], v[76:79], v[48:63]
	ds_read_b64_tr_b16 v[80:81], v246 offset:0x400
	ds_read_b64_tr_b16 v[82:83], v246 offset:0x500
	ds_read_b64_tr_b16 v[84:85], v246 offset:0x1400
	ds_read_b64_tr_b16 v[86:87], v246 offset:0x1500
	ds_read_b64_tr_b16 v[88:89], v246 offset:0x2400
	ds_read_b64_tr_b16 v[90:91], v246 offset:0x2500
	ds_read_b64_tr_b16 v[92:93], v246 offset:0x3400
	ds_read_b64_tr_b16 v[94:95], v246 offset:0x3500
	s_waitcnt lgkmcnt(8)
; #define SBAR() __builtin_amdgcn_sched_barrier(0)
; #define PV_RD2(D0, X) const s16x4 X##l0 = tr_read<v_rd_off2(D0, 0, 0)>(vb), X##h0 = tr_read<v_rd_off2(D0, 0, 1)>(vb), X##l1 = tr_read<v_rd_off2(D0, 1, 0)>(vb), X##h1 = tr_read<v_rd_off2(D0, 1, 1)>(vb), \
;                               X##l2 = tr_read<v_rd_off2(D0, 2, 0)>(vb), X##h2 = tr_read<v_rd_off2(D0, 2, 1)>(vb), X##l3 = tr_read<v_rd_off2(D0, 3, 0)>(vb), X##h3 = tr_read<v_rd_off2(D0, 3, 1)>(vb)
; __device__ __forceinline__ void pv_d02(f32x16* o, int vb, bf16x8 pa0, bf16x8 pa1, bf16x8 pa2, bf16x8 pa3) {
;   PV_RD2(0, a);
;   PV_RD2(1, b); asm volatile("s_waitcnt lgkmcnt(8)" ::: "memory"); SBAR(); PV_MM2(o[0], a); SBAR();
;   PV_RD2(2, c); asm volatile("s_waitcnt lgkmcnt(8)" ::: "memory"); SBAR(); PV_MM2(o[1], b); SBAR();
;   PV_RD2(3, d); asm volatile("s_waitcnt lgkmcnt(8)" ::: "memory"); SBAR(); PV_MM2(o[2], c); SBAR();
;   asm volatile("s_waitcnt lgkmcnt(0)" ::: "memory"); SBAR(); PV_MM2(o[3], d);
; }
; __device__ __forceinline__ void attn_dense_body(const bf16* Qb, const bf16* __restrict__ Kh, const bf16* __restrict__ Vh, const bf16* __restrict__ Zb, ...
;     ...
;   { auto rr = __builtin_amdgcn_permlane32_swap(__float_as_uint(l_reg), __float_as_uint(l_reg), false, false); l_reg = __uint_as_float(rr[0]) + __uint_as_float(rr[1]); }
;   const float rl = __builtin_amdgcn_rcpf(l_reg);
;   { int lb = (wid * QBLK + r32) * LDO + 4 * hi; asm volatile("" : "+v"(lb));
	v_mfma_f32_32x32x16_bf16 v[32:47], v[96:99], v[64:67], v[32:47]
	v_mfma_f32_32x32x16_bf16 v[32:47], v[100:103], v[68:71], v[32:47]
	v_mfma_f32_32x32x16_bf16 v[32:47], v[104:107], v[72:75], v[32:47]
	v_mfma_f32_32x32x16_bf16 v[32:47], v[108:111], v[76:79], v[32:47]
	ds_read_b64_tr_b16 v[96:97], v246 offset:0x600
	ds_read_b64_tr_b16 v[98:99], v246 offset:0x700
	ds_read_b64_tr_b16 v[100:101], v246 offset:0x1600
	ds_read_b64_tr_b16 v[102:103], v246 offset:0x1700
	ds_read_b64_tr_b16 v[104:105], v246 offset:0x2600
	ds_read_b64_tr_b16 v[106:107], v246 offset:0x2700
	ds_read_b64_tr_b16 v[108:109], v246 offset:0x3600
	ds_read_b64_tr_b16 v[110:111], v246 offset:0x3700
	s_waitcnt lgkmcnt(8)
	v_mfma_f32_32x32x16_bf16 v[16:31], v[80:83], v[64:67], v[16:31]
	v_mfma_f32_32x32x16_bf16 v[16:31], v[84:87], v[68:71], v[16:31]
	v_mfma_f32_32x32x16_bf16 v[16:31], v[88:91], v[72:75], v[16:31]
	v_mfma_f32_32x32x16_bf16 v[16:31], v[92:95], v[76:79], v[16:31]
	s_waitcnt lgkmcnt(0)
	v_mfma_f32_32x32x16_bf16 v[0:15], v[96:99], v[64:67], v[0:15]
	v_mov_b32_e32 v64, v112
	s_nop 1
	v_permlane32_swap_b32_e32 v112, v64
	v_add_f32_e32 v64, v112, v64
	s_add_i32 s51, s51, s62
	s_cmp_ge_i32 s51, s6
	v_mfma_f32_32x32x16_bf16 v[0:15], v[100:103], v[68:71], v[0:15]
	v_rcp_f32_e32 v68, v64
	v_lshlrev_b32_e32 v64, 2, v245
	v_lshl_add_u32 v64, v160, 10, v64
	v_ashrrev_i32_e32 v65, 31, v64
	v_lshlrev_b64 v[66:67], 1, v[64:65]
	v_lshl_add_u64 v[64:65], s[24:25], 0, v[66:67]
	v_mfma_f32_32x32x16_bf16 v[0:15], v[104:107], v[72:75], v[0:15]
	v_mfma_f32_32x32x16_bf16 v[0:15], v[108:111], v[76:79], v[0:15]
	v_mul_f32_e32 v48, v48, v68
	v_mul_f32_e32 v49, v49, v68
	v_mul_f32_e32 v50, v50, v68
	v_mul_f32_e32 v51, v51, v68
	v_mul_f32_e32 v52, v52, v68
	v_mul_f32_e32 v53, v53, v68
	v_mul_f32_e32 v54, v54, v68
	v_mul_f32_e32 v55, v55, v68
	v_mul_f32_e32 v56, v56, v68
	v_mul_f32_e32 v57, v57, v68
	v_mul_f32_e32 v58, v58, v68
	v_mul_f32_e32 v59, v59, v68
	v_mul_f32_e32 v60, v60, v68
	v_mul_f32_e32 v61, v61, v68
	v_mul_f32_e32 v62, v62, v68
	v_mul_f32_e32 v63, v63, v68
	v_mul_f32_e32 v32, v32, v68
	v_mul_f32_e32 v33, v33, v68
	v_mul_f32_e32 v34, v34, v68
	v_mul_f32_e32 v35, v35, v68
	v_mul_f32_e32 v36, v36, v68
	v_mul_f32_e32 v37, v37, v68
	v_mul_f32_e32 v38, v38, v68
	v_mul_f32_e32 v39, v39, v68
	v_mul_f32_e32 v40, v40, v68
	v_mul_f32_e32 v41, v41, v68
	v_mul_f32_e32 v42, v42, v68
	v_mul_f32_e32 v43, v43, v68
	v_mul_f32_e32 v44, v44, v68
	v_mul_f32_e32 v45, v45, v68
	v_mul_f32_e32 v46, v46, v68
	v_mul_f32_e32 v47, v47, v68
	v_mul_f32_e32 v16, v16, v68
	v_mul_f32_e32 v17, v17, v68
	v_mul_f32_e32 v18, v18, v68
	v_mul_f32_e32 v19, v19, v68
	v_mul_f32_e32 v20, v20, v68
	v_mul_f32_e32 v21, v21, v68
	v_mul_f32_e32 v22, v22, v68
	v_mul_f32_e32 v23, v23, v68
	v_mul_f32_e32 v24, v24, v68
	v_mul_f32_e32 v25, v25, v68
	v_mul_f32_e32 v26, v26, v68
	v_mul_f32_e32 v27, v27, v68
	v_mul_f32_e32 v28, v28, v68
	v_mul_f32_e32 v29, v29, v68
	v_mul_f32_e32 v30, v30, v68
	v_mul_f32_e32 v31, v31, v68
	v_mul_f32_e32 v0, v0, v68
	v_mul_f32_e32 v1, v1, v68
	v_mul_f32_e32 v2, v2, v68
	v_mul_f32_e32 v3, v3, v68
	v_mul_f32_e32 v4, v4, v68
	v_mul_f32_e32 v5, v5, v68
	v_mul_f32_e32 v6, v6, v68
	v_mul_f32_e32 v7, v7, v68
	v_mul_f32_e32 v8, v8, v68
	v_mul_f32_e32 v9, v9, v68
	v_mul_f32_e32 v10, v10, v68
	v_mul_f32_e32 v11, v11, v68
	v_mul_f32_e32 v12, v12, v68
	v_mul_f32_e32 v13, v13, v68
	v_mul_f32_e32 v14, v14, v68
	v_mul_f32_e32 v15, v15, v68
	s_waitcnt vmcnt(0)
; __device__ __forceinline__ unsigned cvtpk(float lo, float hi) { return pg8::cvt_pk_bf16(lo, hi); }
; __device__ __forceinline__ void attn_dense_body(const bf16* Qb, const bf16* __restrict__ Kh, const bf16* __restrict__ Vh, const bf16* __restrict__ Zb, ...
;     ...
;   { int lb = (wid * QBLK + r32) * LDO + 4 * hi; asm volatile("" : "+v"(lb));
;     unsigned short* Ow = (unsigned short*)Ob + lb; const unsigned short* Zw = (const unsigned short*)Zb + lb;
; #pragma unroll
;     for (int d0 = 0; d0 < 4; ++d0)
; #pragma unroll
;       for (int g = 0; g < 4; ++g) { const int co = d0 * 32 + 8 * g; const unsigned long long zz = *(const unsigned long long*)(Zw + co);
;         const float z0 = __uint_as_float((unsigned)(zz << 16)), z1 = __uint_as_float((unsigned)zz & 0xffff0000u), z2 = __uint_as_float((unsigned)(zz >> 32) << 16), z3 = __uint_as_float((unsigned)(zz >> 32) & 0xffff0000u);
;         const unsigned w0 = cvtpk(o[d0][4 * g + 0] * rl * z0, o[d0][4 * g + 1] * rl * z1), w1 = cvtpk(o[d0][4 * g + 2] * rl * z2, o[d0][4 * g + 3] * rl * z3);
;         *(unsigned long long*)(Ow + co) = (unsigned long long)w0 | ((unsigned long long)w1 << 32); } }
	v_lshlrev_b32_e32 v194, 16, v162
	v_and_b32_e32 v195, 0xffff0000, v162
	v_lshlrev_b32_e32 v196, 16, v163
	v_and_b32_e32 v197, 0xffff0000, v163
	v_mul_f32_e32 v48, v48, v194
	v_mul_f32_e32 v49, v49, v195
	v_mul_f32_e32 v50, v50, v196
	v_mul_f32_e32 v51, v51, v197
	v_cvt_pk_bf16_f32 v48, v48, v49
	v_cvt_pk_bf16_f32 v49, v50, v51
	global_store_dwordx2 v[64:65], v[48:49], off
	v_lshlrev_b32_e32 v194, 16, v164
	v_and_b32_e32 v195, 0xffff0000, v164
	v_lshlrev_b32_e32 v196, 16, v165
	v_and_b32_e32 v197, 0xffff0000, v165
	v_mul_f32_e32 v52, v52, v194
	v_mul_f32_e32 v53, v53, v195
	v_mul_f32_e32 v54, v54, v196
	v_mul_f32_e32 v55, v55, v197
	v_cvt_pk_bf16_f32 v52, v52, v53
	v_cvt_pk_bf16_f32 v53, v54, v55
	global_store_dwordx2 v[64:65], v[52:53], off offset:16
	v_lshlrev_b32_e32 v194, 16, v166
	v_and_b32_e32 v195, 0xffff0000, v166
	v_lshlrev_b32_e32 v196, 16, v167
	v_and_b32_e32 v197, 0xffff0000, v167
	v_mul_f32_e32 v56, v56, v194
	v_mul_f32_e32 v57, v57, v195
	v_mul_f32_e32 v58, v58, v196
	v_mul_f32_e32 v59, v59, v197
	v_cvt_pk_bf16_f32 v56, v56, v57
	v_cvt_pk_bf16_f32 v57, v58, v59
	global_store_dwordx2 v[64:65], v[56:57], off offset:32
	v_lshlrev_b32_e32 v194, 16, v168
	v_and_b32_e32 v195, 0xffff0000, v168
	v_lshlrev_b32_e32 v196, 16, v169
	v_and_b32_e32 v197, 0xffff0000, v169
	v_mul_f32_e32 v60, v60, v194
	v_mul_f32_e32 v61, v61, v195
	v_mul_f32_e32 v62, v62, v196
	v_mul_f32_e32 v63, v63, v197
	v_cvt_pk_bf16_f32 v60, v60, v61
	v_cvt_pk_bf16_f32 v61, v62, v63
	global_store_dwordx2 v[64:65], v[60:61], off offset:48
	v_lshlrev_b32_e32 v194, 16, v170
	v_and_b32_e32 v195, 0xffff0000, v170
	v_lshlrev_b32_e32 v196, 16, v171
	v_and_b32_e32 v197, 0xffff0000, v171
	v_mul_f32_e32 v32, v32, v194
	v_mul_f32_e32 v33, v33, v195
	v_mul_f32_e32 v34, v34, v196
	v_mul_f32_e32 v35, v35, v197
	v_cvt_pk_bf16_f32 v32, v32, v33
	v_cvt_pk_bf16_f32 v33, v34, v35
	global_store_dwordx2 v[64:65], v[32:33], off offset:64
	v_lshlrev_b32_e32 v194, 16, v172
	v_and_b32_e32 v195, 0xffff0000, v172
	v_lshlrev_b32_e32 v196, 16, v173
	v_and_b32_e32 v197, 0xffff0000, v173
	v_mul_f32_e32 v36, v36, v194
	v_mul_f32_e32 v37, v37, v195
	v_mul_f32_e32 v38, v38, v196
	v_mul_f32_e32 v39, v39, v197
	v_cvt_pk_bf16_f32 v36, v36, v37
	v_cvt_pk_bf16_f32 v37, v38, v39
	global_store_dwordx2 v[64:65], v[36:37], off offset:80
	v_lshlrev_b32_e32 v194, 16, v174
	v_and_b32_e32 v195, 0xffff0000, v174
	v_lshlrev_b32_e32 v196, 16, v175
	v_and_b32_e32 v197, 0xffff0000, v175
	v_mul_f32_e32 v40, v40, v194
	v_mul_f32_e32 v41, v41, v195
	v_mul_f32_e32 v42, v42, v196
	v_mul_f32_e32 v43, v43, v197
	v_cvt_pk_bf16_f32 v40, v40, v41
	v_cvt_pk_bf16_f32 v41, v42, v43
	global_store_dwordx2 v[64:65], v[40:41], off offset:96
	v_lshlrev_b32_e32 v194, 16, v176
	v_and_b32_e32 v195, 0xffff0000, v176
	v_lshlrev_b32_e32 v196, 16, v177
	v_and_b32_e32 v197, 0xffff0000, v177
	v_mul_f32_e32 v44, v44, v194
	v_mul_f32_e32 v45, v45, v195
	v_mul_f32_e32 v46, v46, v196
	v_mul_f32_e32 v47, v47, v197
	v_cvt_pk_bf16_f32 v44, v44, v45
	v_cvt_pk_bf16_f32 v45, v46, v47
	global_store_dwordx2 v[64:65], v[44:45], off offset:112
	v_lshlrev_b32_e32 v194, 16, v178
	v_and_b32_e32 v195, 0xffff0000, v178
	v_lshlrev_b32_e32 v196, 16, v179
	v_and_b32_e32 v197, 0xffff0000, v179
	v_mul_f32_e32 v16, v16, v194
	v_mul_f32_e32 v17, v17, v195
	v_mul_f32_e32 v18, v18, v196
	v_mul_f32_e32 v19, v19, v197
	v_cvt_pk_bf16_f32 v16, v16, v17
	v_cvt_pk_bf16_f32 v17, v18, v19
	global_store_dwordx2 v[64:65], v[16:17], off offset:128
	v_lshlrev_b32_e32 v194, 16, v180
	v_and_b32_e32 v195, 0xffff0000, v180
	v_lshlrev_b32_e32 v196, 16, v181
	v_and_b32_e32 v197, 0xffff0000, v181
	v_mul_f32_e32 v20, v20, v194
	v_mul_f32_e32 v21, v21, v195
	v_mul_f32_e32 v22, v22, v196
	v_mul_f32_e32 v23, v23, v197
	v_cvt_pk_bf16_f32 v20, v20, v21
	v_cvt_pk_bf16_f32 v21, v22, v23
	global_store_dwordx2 v[64:65], v[20:21], off offset:144
	v_lshlrev_b32_e32 v194, 16, v182
	v_and_b32_e32 v195, 0xffff0000, v182
	v_lshlrev_b32_e32 v196, 16, v183
	v_and_b32_e32 v197, 0xffff0000, v183
	v_mul_f32_e32 v24, v24, v194
	v_mul_f32_e32 v25, v25, v195
	v_mul_f32_e32 v26, v26, v196
	v_mul_f32_e32 v27, v27, v197
	v_cvt_pk_bf16_f32 v24, v24, v25
	v_cvt_pk_bf16_f32 v25, v26, v27
	global_store_dwordx2 v[64:65], v[24:25], off offset:160
	v_lshlrev_b32_e32 v194, 16, v184
	v_and_b32_e32 v195, 0xffff0000, v184
	v_lshlrev_b32_e32 v196, 16, v185
	v_and_b32_e32 v197, 0xffff0000, v185
	v_mul_f32_e32 v28, v28, v194
	v_mul_f32_e32 v29, v29, v195
	v_mul_f32_e32 v30, v30, v196
	v_mul_f32_e32 v31, v31, v197
	v_cvt_pk_bf16_f32 v28, v28, v29
	v_cvt_pk_bf16_f32 v29, v30, v31
	global_store_dwordx2 v[64:65], v[28:29], off offset:176
	v_lshlrev_b32_e32 v194, 16, v186
	v_and_b32_e32 v195, 0xffff0000, v186
	v_lshlrev_b32_e32 v196, 16, v187
	v_and_b32_e32 v197, 0xffff0000, v187
	v_mul_f32_e32 v0, v0, v194
	v_mul_f32_e32 v1, v1, v195
	v_mul_f32_e32 v2, v2, v196
	v_mul_f32_e32 v3, v3, v197
	v_cvt_pk_bf16_f32 v0, v0, v1
	v_cvt_pk_bf16_f32 v1, v2, v3
	global_store_dwordx2 v[64:65], v[0:1], off offset:192
	v_lshlrev_b32_e32 v194, 16, v188
	v_and_b32_e32 v195, 0xffff0000, v188
	v_lshlrev_b32_e32 v196, 16, v189
	v_and_b32_e32 v197, 0xffff0000, v189
	v_mul_f32_e32 v4, v4, v194
	v_mul_f32_e32 v5, v5, v195
	v_mul_f32_e32 v6, v6, v196
	v_mul_f32_e32 v7, v7, v197
	v_cvt_pk_bf16_f32 v4, v4, v5
	v_cvt_pk_bf16_f32 v5, v6, v7
	global_store_dwordx2 v[64:65], v[4:5], off offset:208
	v_lshlrev_b32_e32 v194, 16, v190
	v_and_b32_e32 v195, 0xffff0000, v190
	v_lshlrev_b32_e32 v196, 16, v191
	v_and_b32_e32 v197, 0xffff0000, v191
	v_mul_f32_e32 v8, v8, v194
	v_mul_f32_e32 v9, v9, v195
	v_mul_f32_e32 v10, v10, v196
	v_mul_f32_e32 v11, v11, v197
	v_cvt_pk_bf16_f32 v8, v8, v9
	v_cvt_pk_bf16_f32 v9, v10, v11
	global_store_dwordx2 v[64:65], v[8:9], off offset:224
	v_lshlrev_b32_e32 v194, 16, v192
	v_and_b32_e32 v195, 0xffff0000, v192
	v_lshlrev_b32_e32 v196, 16, v193
	v_and_b32_e32 v197, 0xffff0000, v193
	v_mul_f32_e32 v12, v12, v194
	v_mul_f32_e32 v13, v13, v195
	v_mul_f32_e32 v14, v14, v196
	v_mul_f32_e32 v15, v15, v197
	v_cvt_pk_bf16_f32 v12, v12, v13
	v_cvt_pk_bf16_f32 v13, v14, v15
	global_store_dwordx2 v[64:65], v[12:13], off offset:240
	s_cbranch_scc0 .LBB0_112
	v_readlane_b32 s84, v255, 16
	v_readlane_b32 s85, v255, 17
	v_readlane_b32 s86, v255, 18
	v_readlane_b32 s87, v255, 19
	s_nop 3
